# code placement: the four GEMM K-loop heads pinned to 64-byte alignment (.p2align 6)
# baseline (speedup 1.0000x reference)
.LBB0_45:
	s_andn2_b64 vcc, exec, s[14:15]
	v_mov_b64_e32 v[0:1], 0
	v_mov_b64_e32 v[2:3], 0
	v_mov_b64_e32 v[4:5], 0
	v_mov_b64_e32 v[6:7], 0
	v_mov_b64_e32 v[8:9], 0
	v_mov_b64_e32 v[10:11], 0
	v_mov_b64_e32 v[12:13], 0
	v_mov_b64_e32 v[14:15], 0
	v_mov_b64_e32 v[16:17], 0
	v_mov_b64_e32 v[18:19], 0
	v_mov_b64_e32 v[20:21], 0
	v_mov_b64_e32 v[22:23], 0
	v_mov_b64_e32 v[24:25], 0
	v_mov_b64_e32 v[26:27], 0
	v_mov_b64_e32 v[28:29], 0
	v_mov_b64_e32 v[30:31], 0
	v_mov_b64_e32 v[32:33], 0
	v_mov_b64_e32 v[34:35], 0
	v_mov_b64_e32 v[36:37], 0
	v_mov_b64_e32 v[38:39], 0
	v_mov_b64_e32 v[40:41], 0
	v_mov_b64_e32 v[42:43], 0
	v_mov_b64_e32 v[44:45], 0
	v_mov_b64_e32 v[46:47], 0
	v_mov_b64_e32 v[48:49], 0
	v_mov_b64_e32 v[50:51], 0
	v_mov_b64_e32 v[52:53], 0
	v_mov_b64_e32 v[54:55], 0
	v_mov_b64_e32 v[56:57], 0
	v_mov_b64_e32 v[58:59], 0
	v_mov_b64_e32 v[60:61], 0
	v_mov_b64_e32 v[62:63], 0
	v_mov_b64_e32 v[64:65], 0
	v_mov_b64_e32 v[66:67], 0
	v_mov_b64_e32 v[68:69], 0
	v_mov_b64_e32 v[70:71], 0
	v_mov_b64_e32 v[72:73], 0
	v_mov_b64_e32 v[74:75], 0
	v_mov_b64_e32 v[76:77], 0
	v_mov_b64_e32 v[78:79], 0
	v_mov_b64_e32 v[80:81], 0
	v_mov_b64_e32 v[82:83], 0
	v_mov_b64_e32 v[84:85], 0
	v_mov_b64_e32 v[86:87], 0
	v_mov_b64_e32 v[88:89], 0
	v_mov_b64_e32 v[90:91], 0
	v_mov_b64_e32 v[92:93], 0
	v_mov_b64_e32 v[94:95], 0
	v_mov_b64_e32 v[96:97], 0
	v_mov_b64_e32 v[98:99], 0
	v_mov_b64_e32 v[100:101], 0
	v_mov_b64_e32 v[102:103], 0
	v_mov_b64_e32 v[104:105], 0
	v_mov_b64_e32 v[106:107], 0
	v_mov_b64_e32 v[108:109], 0
	v_mov_b64_e32 v[110:111], 0
	v_mov_b64_e32 v[112:113], 0
	v_mov_b64_e32 v[114:115], 0
	v_mov_b64_e32 v[116:117], 0
	v_mov_b64_e32 v[118:119], 0
	v_mov_b64_e32 v[120:121], 0
	v_mov_b64_e32 v[122:123], 0
	v_mov_b64_e32 v[124:125], 0
	v_mov_b64_e32 v[126:127], 0
	s_cbranch_vccnz .LBB0_49
	s_add_u32 s0, s28, 0x80
	s_addc_u32 s1, s29, 0
	s_add_u32 s28, s26, 0x100
	s_addc_u32 s29, s27, 0
	s_mov_b32 s26, 0
	.p2align	6

.LBB0_101:
	s_andn2_b64 vcc, exec, s[14:15]
	v_mov_b64_e32 v[0:1], 0
	v_mov_b64_e32 v[2:3], 0
	v_mov_b64_e32 v[4:5], 0
	v_mov_b64_e32 v[6:7], 0
	v_mov_b64_e32 v[8:9], 0
	v_mov_b64_e32 v[10:11], 0
	v_mov_b64_e32 v[12:13], 0
	v_mov_b64_e32 v[14:15], 0
	v_mov_b64_e32 v[16:17], 0
	v_mov_b64_e32 v[18:19], 0
	v_mov_b64_e32 v[20:21], 0
	v_mov_b64_e32 v[22:23], 0
	v_mov_b64_e32 v[24:25], 0
	v_mov_b64_e32 v[26:27], 0
	v_mov_b64_e32 v[28:29], 0
	v_mov_b64_e32 v[30:31], 0
	v_mov_b64_e32 v[32:33], 0
	v_mov_b64_e32 v[34:35], 0
	v_mov_b64_e32 v[36:37], 0
	v_mov_b64_e32 v[38:39], 0
	v_mov_b64_e32 v[40:41], 0
	v_mov_b64_e32 v[42:43], 0
	v_mov_b64_e32 v[44:45], 0
	v_mov_b64_e32 v[46:47], 0
	v_mov_b64_e32 v[48:49], 0
	v_mov_b64_e32 v[50:51], 0
	v_mov_b64_e32 v[52:53], 0
	v_mov_b64_e32 v[54:55], 0
	v_mov_b64_e32 v[56:57], 0
	v_mov_b64_e32 v[58:59], 0
	v_mov_b64_e32 v[60:61], 0
	v_mov_b64_e32 v[62:63], 0
	v_mov_b64_e32 v[64:65], 0
	v_mov_b64_e32 v[66:67], 0
	v_mov_b64_e32 v[68:69], 0
	v_mov_b64_e32 v[70:71], 0
	v_mov_b64_e32 v[72:73], 0
	v_mov_b64_e32 v[74:75], 0
	v_mov_b64_e32 v[76:77], 0
	v_mov_b64_e32 v[78:79], 0
	v_mov_b64_e32 v[80:81], 0
	v_mov_b64_e32 v[82:83], 0
	v_mov_b64_e32 v[84:85], 0
	v_mov_b64_e32 v[86:87], 0
	v_mov_b64_e32 v[88:89], 0
	v_mov_b64_e32 v[90:91], 0
	v_mov_b64_e32 v[92:93], 0
	v_mov_b64_e32 v[94:95], 0
	v_mov_b64_e32 v[96:97], 0
	v_mov_b64_e32 v[98:99], 0
	v_mov_b64_e32 v[100:101], 0
	v_mov_b64_e32 v[102:103], 0
	v_mov_b64_e32 v[104:105], 0
	v_mov_b64_e32 v[106:107], 0
	v_mov_b64_e32 v[108:109], 0
	v_mov_b64_e32 v[110:111], 0
	v_mov_b64_e32 v[112:113], 0
	v_mov_b64_e32 v[114:115], 0
	v_mov_b64_e32 v[116:117], 0
	v_mov_b64_e32 v[118:119], 0
	v_mov_b64_e32 v[120:121], 0
	v_mov_b64_e32 v[122:123], 0
	v_mov_b64_e32 v[124:125], 0
	v_mov_b64_e32 v[126:127], 0
	s_cbranch_vccnz .LBB0_105
	s_add_u32 s24, s24, 0x80
	s_addc_u32 s25, s25, 0
	s_add_u32 s54, s26, 0x100
	s_addc_u32 s55, s27, 0
	s_mov_b32 s26, 0
	.p2align	6
